# v52 + MLA loop: all 12 K-fragment reads issued before the softmax block (v_add3 bases + immediates), row sum accumulated directly into l, 20 MFMAs per step back to back
# speedup vs baseline: 1.0045x; 1.0045x over previous
; DI float bf2f(unsigned short h) { return __uint_as_float((unsigned)h << 16); }
; DI unsigned cvtpk(float lo, float hi) { unsigned r; asm volatile("v_cvt_pk_bf16_f32 %0, %1, %2" : "=v"(r) : "v"(lo), "v"(hi)); return r; }
; DI float swap_sum(float v) { auto rr = __builtin_amdgcn_permlane32_swap(__float_as_uint(v), __float_as_uint(v), false, false); return __uint_as_float(rr[0]) + __uint_as_float(rr[1]); }
; DI void expsum(f32x16& p, float& l_reg, bf16x8& pa0, bf16x8& pa1) {
; #pragma unroll
;     for (int r = 0; r < 16; ++r) p[r] = __builtin_amdgcn_exp2f(p[r]);
;     float ps = 0.f;
; #pragma unroll
;     for (int r = 0; r < 16; ++r) ps += p[r];
;     l_reg += ps; asm volatile("" : "+v"(l_reg));
;     ...
;     ATT_PK4(p, 0, pa0); ATT_PK4(p, 8, pa1);
;     ...
; }
; template <int DQK, int MODE, int LDQ, int LDK, int LDV> ...
;     ...
;     ATT_DMA_K(0); ATT_DMA_K(1); ATT_DMA_V(0, 0); ATT_DMA_K(2); ATT_DMA_V(1, 1);
;     bf16x8 qr[ND0];
;     { const bf16_t* Qw = Qb + (size_t)(wid * 32 + r32) * LDQ + hi * 8;
; #pragma unroll
;       for (int d0 = 0; d0 < ND0; ++d0) qr[d0] = *(const bf16x8*)(Qw + d0 * 16);
;       if constexpr (MODE == 0) {
;           float ss = 0.f;
; #pragma unroll
;           for (int d0 = 0; d0 < ND0; ++d0)
; #pragma unroll
;               for (int j = 0; j < 8; ++j) { const float f = bf2f((unsigned short)qr[d0][j]); ss += f * f; }
;           ss = swap_sum(ss);
;           const float rstd = rsqrtf(ss * (1.f / DQK) + EPS) * C;
; #pragma unroll
;           for (int d0 = 0; d0 < ND0; ++d0) { const float* g = gq + d0 * 16 + hi * 8;
;               { float f[8]; _Pragma("unroll") for (int j = 0; j < 8; ++j) f[j] = bf2f((unsigned short)qr[d0][j]) * rstd * g[j];
;                 u32x4 w = {cvtpk(f[0], f[1]), cvtpk(f[2], f[3]), cvtpk(f[4], f[5]), cvtpk(f[6], f[7])}; qr[d0] = __builtin_bit_cast(bf16x8, w); asm volatile("" ::: "memory"); } }
;       } }
;     const int qlo = q0 + wid * 32, qpos = qlo + r32;
;     const int tL = MODE == 0 ? 0 : (qlo >= 191 ? (qlo - 127) >> 6 : 0), tR = MODE == 0 ? NT : min(NT, (qlo + 222) >> 6);
;     float fL = 1.f, fR = 1.f; if constexpr (MODE != 0) { fL = __builtin_amdgcn_exp2f(bt[0]); fR = __builtin_amdgcn_exp2f(-bt[448]); }
;     ...
;     const int vbase = (int)(unsigned)(size_t)lds + V_OFF + v_rd_base(lane);
;     ...
;     constexpr int NDA = ND0 > 6 ? 6 : ND0;
.Lstg_mla_top_2:
	s_setprio 0
	s_mov_b32 m0, s1
	s_mov_b32 s0, s5
	s_mov_b32 s5, s44
	s_mov_b32 s44, s4
	s_lshl_b32 s4, s4, 14
	global_load_lds_dwordx4 v136, s[34:35]
	s_add_i32 m0, s1, 0x2000
	s_add_i32 s4, s52, s4
	global_load_lds_dwordx4 v138, s[34:35]
	s_add_i32 m0, s1, 0x4000
	s_add_i32 s6, s4, 0x400
	global_load_lds_dwordx4 v140, s[34:35]
	s_mov_b32 m0, s4
	s_add_i32 s1, s43, -3
	global_load_lds_dwordx4 v144, s[34:35]
	s_mov_b32 m0, s6
	s_nop 0
	global_load_lds_dwordx4 v142, s[34:35]
	s_and_b32 s1, s1, 3
	s_mulk_i32 s1, 0x6000
	v_add3_u32 v174, s1, v158, v151
	v_add3_u32 v178, s1, v158, v149
	v_add3_u32 v182, s1, v158, v148
	v_add3_u32 v186, s1, v158, v147
	s_lshl_b32 s1, s0, 14
	ds_read_b128 v[190:193], v174 offset:12416
	ds_read_b128 v[194:197], v178 offset:12416
	ds_read_b128 v[230:233], v182 offset:12416
	ds_read_b128 v[234:237], v186 offset:12416
	ds_read_b128 v[238:241], v174 offset:12544
	ds_read_b128 v[242:245], v178 offset:12544
	ds_read_b128 v[246:249], v182 offset:12544
	ds_read_b128 v[250:253], v186 offset:12544
	ds_read_b128 v[174:177], v174 offset:12288
	ds_read_b128 v[178:181], v178 offset:12288
	ds_read_b128 v[182:185], v182 offset:12288
	ds_read_b128 v[186:189], v186 offset:12288
	v_add_u32_e32 v254, s1, v130
	ds_read_b64_tr_b16 v[198:199], v254 offset:0
	ds_read_b64_tr_b16 v[200:201], v254 offset:0x800
	ds_read_b64_tr_b16 v[202:203], v254 offset:0x1000
	ds_read_b64_tr_b16 v[204:205], v254 offset:0x1800
	ds_read_b64_tr_b16 v[206:207], v254 offset:0x200
	ds_read_b64_tr_b16 v[208:209], v254 offset:0xa00
	ds_read_b64_tr_b16 v[210:211], v254 offset:0x1200
	ds_read_b64_tr_b16 v[212:213], v254 offset:0x1a00
	ds_read_b64_tr_b16 v[214:215], v254 offset:0x400
	ds_read_b64_tr_b16 v[216:217], v254 offset:0xc00
	ds_read_b64_tr_b16 v[218:219], v254 offset:0x1400
	ds_read_b64_tr_b16 v[220:221], v254 offset:0x1c00
	ds_read_b64_tr_b16 v[222:223], v254 offset:0x600
	ds_read_b64_tr_b16 v[224:225], v254 offset:0xe00
	ds_read_b64_tr_b16 v[226:227], v254 offset:0x1600
	ds_read_b64_tr_b16 v[228:229], v254 offset:0x1e00
	s_setprio 2
	v_exp_f32_e32 v64, v64
	v_exp_f32_e32 v65, v65
	v_exp_f32_e32 v66, v66
	v_exp_f32_e32 v67, v67
	v_exp_f32_e32 v68, v68
	v_exp_f32_e32 v69, v69
	v_add_f32_e32 v173, v64, v173
	v_add_f32_e32 v173, v65, v173
	v_exp_f32_e32 v70, v70
	v_add_f32_e32 v173, v66, v173
	v_exp_f32_e32 v71, v71
	v_add_f32_e32 v173, v67, v173
	v_exp_f32_e32 v72, v72
	v_add_f32_e32 v173, v68, v173
	v_exp_f32_e32 v73, v73
	v_add_f32_e32 v173, v69, v173
	v_exp_f32_e32 v74, v74
	v_add_f32_e32 v173, v70, v173
	v_exp_f32_e32 v75, v75
	v_add_f32_e32 v173, v71, v173
	v_exp_f32_e32 v76, v76
	v_add_f32_e32 v173, v72, v173
	v_exp_f32_e32 v77, v77
	v_add_f32_e32 v173, v73, v173
	v_exp_f32_e32 v78, v78
	v_add_f32_e32 v173, v74, v173
	v_exp_f32_e32 v79, v79
	v_add_f32_e32 v173, v75, v173
	v_add_f32_e32 v173, v76, v173
	v_add_f32_e32 v173, v77, v173
	v_add_f32_e32 v173, v78, v173
	v_add_f32_e32 v173, v79, v173
	v_cvt_pk_bf16_f32 v64, v64, v65
	v_cvt_pk_bf16_f32 v65, v66, v67
	v_cvt_pk_bf16_f32 v66, v68, v69
	v_cvt_pk_bf16_f32 v67, v70, v71
	v_cvt_pk_bf16_f32 v68, v72, v73
	v_cvt_pk_bf16_f32 v69, v74, v75
	v_cvt_pk_bf16_f32 v70, v76, v77
	v_cvt_pk_bf16_f32 v71, v78, v79
	s_nop 0
	v_permlane32_swap_b32_e32 v64, v66
	v_permlane32_swap_b32_e32 v65, v67
	v_permlane32_swap_b32_e32 v68, v70
	v_permlane32_swap_b32_e32 v69, v71
	s_waitcnt lgkmcnt(0)
; #define LAS __attribute__((address_space(3)))
; #define SBAR() __builtin_amdgcn_sched_barrier(0)
; #define ATT_DMA_K(t) do { const bf16_t* kg_ = Kh + (size_t)(t) * 64 * LDK; LAS unsigned char* sb_ = lds + ((t) & 3) * KBUF; \
;     _Pragma("unroll") for (int i_ = 0; i_ < NKP; ++i_) __builtin_amdgcn_global_load_lds((const unsigned*)(kg_ + kgo[i_]), (LAS unsigned*)(sb_ + (wid + 8 * i_) * 1024), 16, 0, 0); } while (0)
; DI void pv_mma(f32x16* o, const s16x4* vf, bf16x8 pa0, bf16x8 pa1) {
;     ...
; #pragma unroll
;     for (int d0 = 0; d0 < 4; ++d0) {
;         o[d0] = __builtin_amdgcn_mfma_f32_32x32x16_bf16(pa0, ATT_PK(vf[4 * d0], vf[4 * d0 + 1]), o[d0], 0, 0, 0);
;         o[d0] = __builtin_amdgcn_mfma_f32_32x32x16_bf16(pa1, ATT_PK(vf[4 * d0 + 2], vf[4 * d0 + 3]), o[d0], 0, 0, 0); }
;     ...
; }
; template <int DQK, int D0A, int D0B> DI void k_reads(bf16x8* kf, const LAS unsigned char* Ks, int half, int r32, int hi) {
; #pragma unroll
;     for (int d0 = D0A; d0 < D0B; ++d0) kf[d0 - D0A] = *(const LAS bf16x8*)(Ks + half * (32 * DQK * 2) + kswz<DQK>(r32, (d0 * 16 + hi * 8) * 2));
; }
; template <int D0A, int D0B> DI void qk_mma(f32x16& p, const bf16x8* kf, const bf16x8* qr) {
; #pragma unroll
;     for (int d0 = D0A; d0 < D0B; ++d0) {
;         if (d0 == 0) { f32x16 z; _Pragma("unroll") for (int r = 0; r < 16; ++r) z[r] = 0.f; p = __builtin_amdgcn_mfma_f32_32x32x16_bf16(kf[0], qr[0], z, 0, 0, 0); }
;         else p = __builtin_amdgcn_mfma_f32_32x32x16_bf16(kf[d0 - D0A], qr[d0], p, 0, 0, 0); }
; }
; template <int DQK, int MODE, int LDQ, int LDK, int LDV> ...
;     ...
;     f32x16 pA, pB; bf16x8 pa0, pa1;
;     int v0 = 0, v1 = 1, v2 = 2;
;     ATT_TOP(NKP + 2);
;     { bf16x8 kf[NDA]; k_reads<DQK, 0, NDA>(kf, lds, 0, r32, hi); ATT_LGKM0(); qk_mma<0, NDA>(pA, kf, qr);
;       if constexpr (ND0 > NDA) { bf16x8 kg[ND0 - NDA]; k_reads<DQK, NDA, ND0>(kg, lds, 0, r32, hi); ATT_LGKM0(); qk_mma<NDA, ND0>(pA, kg, qr); }
;       ATT_BIAS(pA, 0, 0); }
;     if (wid >= 4) __builtin_amdgcn_s_setprio(1);
;     for (int j = 0; j < NT; ++j) {
;         if (j + 2 < NT) ATT_TOP(NKP + 2); else ATT_TOP(0);
;         if (j + 3 < NT) ATT_DMA_K(j + 3);
;         if (j + 2 < NT) ATT_DMA_V(j + 2, v2);
;         ATT_SEG(j); SBAR();
;         ATT_STEP(pA, pB, 0, v0, true, 1, j);
;         ATT_STEP(pB, pA, 1, v0, (j + 1 < NT), 0, j + 1);
	s_setprio 1
	v_mfma_f32_32x32x16_bf16 v[48:63], v[64:67], v[198:201], v[48:63]
	v_mfma_f32_32x32x16_bf16 v[32:47], v[64:67], v[206:209], v[32:47]
	v_mfma_f32_32x32x16_bf16 v[16:31], v[64:67], v[214:217], v[16:31]
	v_mfma_f32_32x32x16_bf16 v[0:15], v[64:67], v[222:225], v[0:15]
	v_mfma_f32_32x32x16_bf16 v[48:63], v[68:71], v[202:205], v[48:63]
	v_mfma_f32_32x32x16_bf16 v[32:47], v[68:71], v[210:213], v[32:47]
	v_mfma_f32_32x32x16_bf16 v[16:31], v[68:71], v[218:221], v[16:31]
	v_mfma_f32_32x32x16_bf16 v[0:15], v[68:71], v[226:229], v[0:15]
	v_mfma_f32_32x32x16_bf16 v[64:79], v[174:177], v[80:83], 0
	v_mfma_f32_32x32x16_bf16 v[64:79], v[178:181], v[84:87], v[64:79]
	v_mfma_f32_32x32x16_bf16 v[64:79], v[182:185], v[88:91], v[64:79]
	v_mfma_f32_32x32x16_bf16 v[64:79], v[186:189], v[92:95], v[64:79]
	v_mfma_f32_32x32x16_bf16 v[64:79], v[190:193], v[96:99], v[64:79]
	v_mfma_f32_32x32x16_bf16 v[64:79], v[194:197], v[100:103], v[64:79]
	v_mfma_f32_32x32x16_bf16 v[64:79], v[230:233], v[104:107], v[64:79]
	v_mfma_f32_32x32x16_bf16 v[64:79], v[234:237], v[108:111], v[64:79]
	v_mfma_f32_32x32x16_bf16 v[64:79], v[238:241], v[112:115], v[64:79]
	v_mfma_f32_32x32x16_bf16 v[64:79], v[242:245], v[116:119], v[64:79]
	v_mfma_f32_32x32x16_bf16 v[64:79], v[246:249], v[120:123], v[64:79]
	v_mfma_f32_32x32x16_bf16 v[64:79], v[250:253], v[124:127], v[64:79]
	s_setprio 0
	s_add_i32 s4, s43, -2
	s_and_b32 s4, s4, 3
	s_mulk_i32 s4, 0x6000
	v_add3_u32 v174, s4, v158, v151
	v_add3_u32 v178, s4, v158, v149
	v_add3_u32 v182, s4, v158, v148
	v_add3_u32 v186, s4, v158, v147
	ds_read_b128 v[190:193], v174 offset:128
	ds_read_b128 v[194:197], v178 offset:128
	ds_read_b128 v[230:233], v182 offset:128
	ds_read_b128 v[234:237], v186 offset:128
	ds_read_b128 v[238:241], v174 offset:256
	ds_read_b128 v[242:245], v178 offset:256
	ds_read_b128 v[246:249], v182 offset:256
	ds_read_b128 v[250:253], v186 offset:256
	ds_read_b128 v[174:177], v174
	ds_read_b128 v[178:181], v178
	ds_read_b128 v[182:185], v182
	ds_read_b128 v[186:189], v186
	ds_read_b64_tr_b16 v[198:199], v254 offset:0x2000
	ds_read_b64_tr_b16 v[200:201], v254 offset:0x2800
	ds_read_b64_tr_b16 v[202:203], v254 offset:0x3000
	ds_read_b64_tr_b16 v[204:205], v254 offset:0x3800
	ds_read_b64_tr_b16 v[206:207], v254 offset:0x2200
	ds_read_b64_tr_b16 v[208:209], v254 offset:0x2a00
	ds_read_b64_tr_b16 v[210:211], v254 offset:0x3200
	ds_read_b64_tr_b16 v[212:213], v254 offset:0x3a00
	ds_read_b64_tr_b16 v[214:215], v254 offset:0x2400
	ds_read_b64_tr_b16 v[216:217], v254 offset:0x2c00
	ds_read_b64_tr_b16 v[218:219], v254 offset:0x3400
	ds_read_b64_tr_b16 v[220:221], v254 offset:0x3c00
	ds_read_b64_tr_b16 v[222:223], v254 offset:0x2600
	ds_read_b64_tr_b16 v[224:225], v254 offset:0x2e00
	ds_read_b64_tr_b16 v[226:227], v254 offset:0x3600
	ds_read_b64_tr_b16 v[228:229], v254 offset:0x3e00
	s_setprio 2
	v_exp_f32_e32 v64, v64
	v_exp_f32_e32 v65, v65
	v_exp_f32_e32 v66, v66
	v_exp_f32_e32 v67, v67
	v_exp_f32_e32 v68, v68
	v_exp_f32_e32 v69, v69
	v_add_f32_e32 v173, v64, v173
	v_add_f32_e32 v173, v65, v173
	v_exp_f32_e32 v70, v70
	v_add_f32_e32 v173, v66, v173
	v_exp_f32_e32 v71, v71
	v_add_f32_e32 v173, v67, v173
	v_exp_f32_e32 v72, v72
	v_add_f32_e32 v173, v68, v173
	v_exp_f32_e32 v73, v73
	v_add_f32_e32 v173, v69, v173
	v_exp_f32_e32 v74, v74
	v_add_f32_e32 v173, v70, v173
	v_exp_f32_e32 v75, v75
	v_add_f32_e32 v173, v71, v173
	v_exp_f32_e32 v76, v76
	v_add_f32_e32 v173, v72, v173
	v_exp_f32_e32 v77, v77
	v_add_f32_e32 v173, v73, v173
	v_exp_f32_e32 v78, v78
	v_add_f32_e32 v173, v74, v173
	v_exp_f32_e32 v79, v79
	v_add_f32_e32 v173, v75, v173
	v_add_f32_e32 v173, v76, v173
	v_add_f32_e32 v173, v77, v173
	v_add_f32_e32 v173, v78, v173
	v_add_f32_e32 v173, v79, v173
	v_cvt_pk_bf16_f32 v64, v64, v65
	v_cvt_pk_bf16_f32 v65, v66, v67
	v_cvt_pk_bf16_f32 v66, v68, v69
	v_cvt_pk_bf16_f32 v67, v70, v71
	v_cvt_pk_bf16_f32 v68, v72, v73
	v_cvt_pk_bf16_f32 v69, v74, v75
	v_cvt_pk_bf16_f32 v70, v76, v77
	v_cvt_pk_bf16_f32 v71, v78, v79
	s_nop 0
	v_permlane32_swap_b32_e32 v64, v66
	v_permlane32_swap_b32_e32 v65, v67
	v_permlane32_swap_b32_e32 v68, v70
	v_permlane32_swap_b32_e32 v69, v71
	s_waitcnt lgkmcnt(0)
	s_setprio 1
	s_cmp_lt_u32 s33, 0x100
	s_cbranch_scc1 .Lstg_mla_mid_3
	s_waitcnt vmcnt(5)
	s_barrier
.Lstg_mla_mid_3:
	v_mfma_f32_32x32x16_bf16 v[48:63], v[64:67], v[198:201], v[48:63]
	v_mfma_f32_32x32x16_bf16 v[32:47], v[64:67], v[206:209], v[32:47]
	v_mfma_f32_32x32x16_bf16 v[16:31], v[64:67], v[214:217], v[16:31]
	v_mfma_f32_32x32x16_bf16 v[0:15], v[64:67], v[222:225], v[0:15]
	v_mfma_f32_32x32x16_bf16 v[48:63], v[68:71], v[202:205], v[48:63]
	v_mfma_f32_32x32x16_bf16 v[32:47], v[68:71], v[210:213], v[32:47]
	v_mfma_f32_32x32x16_bf16 v[16:31], v[68:71], v[218:221], v[16:31]
	v_mfma_f32_32x32x16_bf16 v[0:15], v[68:71], v[226:229], v[0:15]
	v_mfma_f32_32x32x16_bf16 v[64:79], v[174:177], v[80:83], 0
	v_mfma_f32_32x32x16_bf16 v[64:79], v[178:181], v[84:87], v[64:79]
	v_mfma_f32_32x32x16_bf16 v[64:79], v[182:185], v[88:91], v[64:79]
	v_mfma_f32_32x32x16_bf16 v[64:79], v[186:189], v[92:95], v[64:79]
	v_mfma_f32_32x32x16_bf16 v[64:79], v[190:193], v[96:99], v[64:79]
	v_mfma_f32_32x32x16_bf16 v[64:79], v[194:197], v[100:103], v[64:79]
	v_mfma_f32_32x32x16_bf16 v[64:79], v[230:233], v[104:107], v[64:79]
	v_mfma_f32_32x32x16_bf16 v[64:79], v[234:237], v[108:111], v[64:79]
	v_mfma_f32_32x32x16_bf16 v[64:79], v[238:241], v[112:115], v[64:79]
	v_mfma_f32_32x32x16_bf16 v[64:79], v[242:245], v[116:119], v[64:79]
	v_mfma_f32_32x32x16_bf16 v[64:79], v[246:249], v[120:123], v[64:79]
	v_mfma_f32_32x32x16_bf16 v[64:79], v[250:253], v[124:127], v[64:79]
	s_add_i32 s43, s43, 1
	v_add_u32_e32 v136, s36, v136
	v_add_u32_e32 v138, s36, v138
	v_add_u32_e32 v140, s36, v140
	v_add_u32_e32 v142, s38, v142
	v_add_u32_e32 v144, s38, v144
	s_cmp_eq_u32 s43, 64
	s_mov_b32 s4, s0
	s_cbranch_scc0 .LBB0_1982
	s_lshl_b32 s0, s55, 2
	s_add_i32 s4, s0, 0
	s_add_i32 s6, s52, s1
	s_add_i32 s4, s4, 0x24000
	s_add_i32 s7, s6, 0x400
	s_add_u32 s0, s2, 0x3f0000
	s_addc_u32 s1, s3, 0
	s_cmp_lt_u32 s33, 0x100
	s_cbranch_scc0 .Lstg_mla_t61_4
	s_waitcnt vmcnt(5)
	s_barrier
